# local seams now issue buffer_inv sc1 (this CU's L1) at seam entry, overlapped with the wait, instead of the no-op sc0 invalidate
# baseline (speedup 1.0000x reference)
; __device__ __forceinline__ unsigned xb_ld(unsigned* p)              { return __hip_atomic_load(p, __ATOMIC_RELAXED, __HIP_MEMORY_SCOPE_AGENT); }
; __device__ __forceinline__ unsigned xb_add(unsigned* p, unsigned v) { return __hip_atomic_fetch_add(p, v, __ATOMIC_RELAXED, __HIP_MEMORY_SCOPE_AGENT); }
; #define XB_SPIN(cond, bar) do { unsigned _sp = 0; while (cond) { __builtin_amdgcn_s_sleep(1); \
;     if ((++_sp & 255u) == 0u) { if (xb_ld(&(bar)[XB_TMO])) break; if (_sp > XB_SPIN_CAP) { atomicAdd(&(bar)[XB_TMO], 1u); break; } } } } while (0)
; __device__ __forceinline__ void xcd_barrier(const XcdBarrier& b) {
;     asm volatile("s_waitcnt vmcnt(0)" ::: "memory");
;     __syncthreads();
;     if (threadIdx.x == 0) {
;         unsigned* bar = b.bar;
;         __builtin_amdgcn_s_waitcnt(0);
;         unsigned nloc = b.st[0], nx = b.st[1];
;         if (nloc == 0u) { xcd_barrier_complete(bar, b.x, nloc, nx); b.st[0] = nloc; b.st[1] = nx; }
;         const unsigned old = xb_add(&bar[XB_XSUB(b.x)], 1u);
;         const unsigned gen = old / nloc;
;         if (old + 1u == (gen + 1u) * nloc) {
;             __builtin_amdgcn_fence(__ATOMIC_RELEASE, "agent");
;             asm volatile("s_waitcnt vmcnt(0)" ::: "memory");
;             const unsigned og = xb_add(&bar[XB_TOP], 1u);
;             const unsigned tg = og / nx;
;             if (og + 1u == (tg + 1u) * nx) xb_add(&bar[XB_TOPGEN], 1u);
;             else XB_SPIN(xb_ld(&bar[XB_TOPGEN]) == tg, bar);
;             __builtin_amdgcn_fence(__ATOMIC_ACQUIRE, "agent");
;             xb_add(&bar[XB_XGEN(b.x)], 1u);
;             asm volatile("s_waitcnt vmcnt(0)" ::: "memory");
;         } else {
;             XB_SPIN(xb_ld(&bar[XB_XGEN(b.x)]) == gen, bar);
;             __builtin_amdgcn_fence(__ATOMIC_ACQUIRE, "agent");
;             asm volatile("s_waitcnt vmcnt(0)" ::: "memory");
;         }
.LBB0_1679:
	s_cmp_lt_i32 s57, 5
	s_cbranch_scc1 .LBB0_1733
	s_waitcnt vmcnt(0)
	s_waitcnt vmcnt(0) lgkmcnt(0)
	s_barrier
	s_and_saveexec_b64 s[6:7], s[4:5]
	s_cbranch_execz .LBB0_1732
	buffer_inv sc1
	v_mov_b32_e32 v0, 0
	global_load_dwordx4 v[6:9], v0, s[50:51] offset:256 sc1
	global_load_dwordx4 v[10:13], v0, s[50:51] offset:272 sc1
	s_lshl_b32 s3, s33, 8
	s_add_u32 s8, s50, s3
	s_addc_u32 s9, s51, 0
	v_mov_b32_e32 v3, 0x2000
	global_load_dword v4, v3, s[8:9] offset:1024 sc1
	v_mov_b32_e32 v2, 0x20000
	ds_read_b32 v2, v2
	s_waitcnt vmcnt(0) lgkmcnt(0)
	v_add_u32_e32 v14, -1, v6
	v_and_b32_e32 v1, v14, v6
	v_min_u32_e32 v15, v6, v7
	v_add_u32_e32 v14, -1, v7
	v_and_or_b32 v1, v14, v7, v1
	v_min_u32_e32 v15, v15, v8
	v_add_u32_e32 v14, -1, v8
	v_and_or_b32 v1, v14, v8, v1
	v_min_u32_e32 v15, v15, v9
	v_add_u32_e32 v14, -1, v9
	v_and_or_b32 v1, v14, v9, v1
	v_min_u32_e32 v15, v15, v10
	v_add_u32_e32 v14, -1, v10
	v_and_or_b32 v1, v14, v10, v1
	v_min_u32_e32 v15, v15, v11
	v_add_u32_e32 v14, -1, v11
	v_and_or_b32 v1, v14, v11, v1
	v_min_u32_e32 v15, v15, v12
	v_add_u32_e32 v14, -1, v12
	v_and_or_b32 v1, v14, v12, v1
	v_min_u32_e32 v15, v15, v13
	v_add_u32_e32 v14, -1, v13
	v_and_or_b32 v1, v14, v13, v1
	s_nop 0
	v_readfirstlane_b32 s10, v1
	v_readfirstlane_b32 s13, v15
	v_readfirstlane_b32 s11, v4
	v_readfirstlane_b32 s12, v2
	s_nop 1
	s_cmp_lg_u32 s10, 0
	s_cbranch_scc1 .Lseam34_full
	s_cmp_eq_u32 s13, 0
	s_cbranch_scc1 .Lseam34_full
	s_cmpk_lg_i32 s58, 0x100
	s_cbranch_scc1 .Lseam34_full
	s_cmp_eq_u32 s12, 0
	s_cbranch_scc1 .Lseam34_full
	v_mov_b32_e32 v3, 0x1000
	v_mov_b32_e32 v5, 1
	global_atomic_add v3, v3, v5, s[8:9] offset:1024 sc0
	s_waitcnt vmcnt(0)
	v_readfirstlane_b32 s13, v3
	s_add_i32 s14, s11, 1
	s_mul_i32 s14, s14, s12
	s_add_i32 s13, s13, 1
	v_mov_b32_e32 v3, 0x2000
	s_cmp_eq_u32 s13, s14
	s_cbranch_scc1 .Lseam34_lead

; __device__ __forceinline__ unsigned xb_ld(unsigned* p)              { return __hip_atomic_load(p, __ATOMIC_RELAXED, __HIP_MEMORY_SCOPE_AGENT); }
; __device__ __forceinline__ unsigned xb_add(unsigned* p, unsigned v) { return __hip_atomic_fetch_add(p, v, __ATOMIC_RELAXED, __HIP_MEMORY_SCOPE_AGENT); }
; #define XB_SPIN(cond, bar) do { unsigned _sp = 0; while (cond) { __builtin_amdgcn_s_sleep(1); \
;     if ((++_sp & 255u) == 0u) { if (xb_ld(&(bar)[XB_TMO])) break; if (_sp > XB_SPIN_CAP) { atomicAdd(&(bar)[XB_TMO], 1u); break; } } } } while (0)
; __device__ __forceinline__ void xcd_barrier(const XcdBarrier& b) {
;     ...
;             __builtin_amdgcn_fence(__ATOMIC_ACQUIRE, "agent");
;             xb_add(&bar[XB_XGEN(b.x)], 1u);
;             asm volatile("s_waitcnt vmcnt(0)" ::: "memory");
;         } else {
;             XB_SPIN(xb_ld(&bar[XB_XGEN(b.x)]) == gen, bar);
;             __builtin_amdgcn_fence(__ATOMIC_ACQUIRE, "agent");
;             asm volatile("s_waitcnt vmcnt(0)" ::: "memory");
.Lseam34_done:
	s_waitcnt vmcnt(0)
	s_branch .LBB0_1732

; __device__ __forceinline__ unsigned xb_ld(unsigned* p)              { return __hip_atomic_load(p, __ATOMIC_RELAXED, __HIP_MEMORY_SCOPE_AGENT); }
; __device__ __forceinline__ unsigned xb_add(unsigned* p, unsigned v) { return __hip_atomic_fetch_add(p, v, __ATOMIC_RELAXED, __HIP_MEMORY_SCOPE_AGENT); }
; #define XB_SPIN(cond, bar) do { unsigned _sp = 0; while (cond) { __builtin_amdgcn_s_sleep(1); \
;     if ((++_sp & 255u) == 0u) { if (xb_ld(&(bar)[XB_TMO])) break; if (_sp > XB_SPIN_CAP) { atomicAdd(&(bar)[XB_TMO], 1u); break; } } } } while (0)
; __device__ __forceinline__ void xcd_barrier(const XcdBarrier& b) {
;     asm volatile("s_waitcnt vmcnt(0)" ::: "memory");
;     __syncthreads();
;     if (threadIdx.x == 0) {
;         unsigned* bar = b.bar;
;         __builtin_amdgcn_s_waitcnt(0);
;         unsigned nloc = b.st[0], nx = b.st[1];
;         if (nloc == 0u) { xcd_barrier_complete(bar, b.x, nloc, nx); b.st[0] = nloc; b.st[1] = nx; }
;         const unsigned old = xb_add(&bar[XB_XSUB(b.x)], 1u);
;         const unsigned gen = old / nloc;
;         if (old + 1u == (gen + 1u) * nloc) {
;             __builtin_amdgcn_fence(__ATOMIC_RELEASE, "agent");
;             asm volatile("s_waitcnt vmcnt(0)" ::: "memory");
;             const unsigned og = xb_add(&bar[XB_TOP], 1u);
;             const unsigned tg = og / nx;
;             if (og + 1u == (tg + 1u) * nx) xb_add(&bar[XB_TOPGEN], 1u);
;             else XB_SPIN(xb_ld(&bar[XB_TOPGEN]) == tg, bar);
;             __builtin_amdgcn_fence(__ATOMIC_ACQUIRE, "agent");
;             xb_add(&bar[XB_XGEN(b.x)], 1u);
;             asm volatile("s_waitcnt vmcnt(0)" ::: "memory");
;         } else {
;             XB_SPIN(xb_ld(&bar[XB_XGEN(b.x)]) == gen, bar);
;             __builtin_amdgcn_fence(__ATOMIC_ACQUIRE, "agent");
;             asm volatile("s_waitcnt vmcnt(0)" ::: "memory");
;         }
.LBB0_1779:
	s_cmp_lt_i32 s57, 6
	s_cbranch_scc1 .LBB0_1833
	s_waitcnt vmcnt(0)
	s_waitcnt vmcnt(0) lgkmcnt(0)
	s_barrier
	s_and_saveexec_b64 s[6:7], s[4:5]
	s_cbranch_execz .LBB0_1832
	buffer_inv sc1
	v_mov_b32_e32 v0, 0
	global_load_dwordx4 v[6:9], v0, s[50:51] offset:256 sc1
	global_load_dwordx4 v[10:13], v0, s[50:51] offset:272 sc1
	s_lshl_b32 s3, s33, 8
	s_add_u32 s8, s50, s3
	s_addc_u32 s9, s51, 0
	v_mov_b32_e32 v3, 0x2000
	global_load_dword v4, v3, s[8:9] offset:1024 sc1
	v_mov_b32_e32 v2, 0x20000
	ds_read_b32 v2, v2
	s_waitcnt vmcnt(0) lgkmcnt(0)
	v_add_u32_e32 v14, -1, v6
	v_and_b32_e32 v1, v14, v6
	v_min_u32_e32 v15, v6, v7
	v_add_u32_e32 v14, -1, v7
	v_and_or_b32 v1, v14, v7, v1
	v_min_u32_e32 v15, v15, v8
	v_add_u32_e32 v14, -1, v8
	v_and_or_b32 v1, v14, v8, v1
	v_min_u32_e32 v15, v15, v9
	v_add_u32_e32 v14, -1, v9
	v_and_or_b32 v1, v14, v9, v1
	v_min_u32_e32 v15, v15, v10
	v_add_u32_e32 v14, -1, v10
	v_and_or_b32 v1, v14, v10, v1
	v_min_u32_e32 v15, v15, v11
	v_add_u32_e32 v14, -1, v11
	v_and_or_b32 v1, v14, v11, v1
	v_min_u32_e32 v15, v15, v12
	v_add_u32_e32 v14, -1, v12
	v_and_or_b32 v1, v14, v12, v1
	v_min_u32_e32 v15, v15, v13
	v_add_u32_e32 v14, -1, v13
	v_and_or_b32 v1, v14, v13, v1
	s_nop 0
	v_readfirstlane_b32 s10, v1
	v_readfirstlane_b32 s13, v15
	v_readfirstlane_b32 s11, v4
	v_readfirstlane_b32 s12, v2
	s_nop 1
	s_cmp_lg_u32 s10, 0
	s_cbranch_scc1 .Lseam45_full
	s_cmp_eq_u32 s13, 0
	s_cbranch_scc1 .Lseam45_full
	s_cmpk_lg_i32 s58, 0x100
	s_cbranch_scc1 .Lseam45_full
	s_cmp_eq_u32 s12, 0
	s_cbranch_scc1 .Lseam45_full
	v_mov_b32_e32 v3, 0x1000
	v_mov_b32_e32 v5, 1
	global_atomic_add v3, v3, v5, s[8:9] offset:1024 sc0
	s_waitcnt vmcnt(0)
	v_readfirstlane_b32 s13, v3
	s_add_i32 s14, s11, 1
	s_mul_i32 s14, s14, s12
	s_add_i32 s13, s13, 1
	v_mov_b32_e32 v3, 0x2000
	s_cmp_eq_u32 s13, s14
	s_cbranch_scc1 .Lseam45_lead

; __device__ __forceinline__ unsigned xb_ld(unsigned* p)              { return __hip_atomic_load(p, __ATOMIC_RELAXED, __HIP_MEMORY_SCOPE_AGENT); }
; __device__ __forceinline__ unsigned xb_add(unsigned* p, unsigned v) { return __hip_atomic_fetch_add(p, v, __ATOMIC_RELAXED, __HIP_MEMORY_SCOPE_AGENT); }
; #define XB_SPIN(cond, bar) do { unsigned _sp = 0; while (cond) { __builtin_amdgcn_s_sleep(1); \
;     if ((++_sp & 255u) == 0u) { if (xb_ld(&(bar)[XB_TMO])) break; if (_sp > XB_SPIN_CAP) { atomicAdd(&(bar)[XB_TMO], 1u); break; } } } } while (0)
; __device__ __forceinline__ void xcd_barrier(const XcdBarrier& b) {
;     asm volatile("s_waitcnt vmcnt(0)" ::: "memory");
;     __syncthreads();
;     if (threadIdx.x == 0) {
;         unsigned* bar = b.bar;
;         __builtin_amdgcn_s_waitcnt(0);
;         unsigned nloc = b.st[0], nx = b.st[1];
;         if (nloc == 0u) { xcd_barrier_complete(bar, b.x, nloc, nx); b.st[0] = nloc; b.st[1] = nx; }
;         const unsigned old = xb_add(&bar[XB_XSUB(b.x)], 1u);
;         const unsigned gen = old / nloc;
;         if (old + 1u == (gen + 1u) * nloc) {
;             __builtin_amdgcn_fence(__ATOMIC_RELEASE, "agent");
;             asm volatile("s_waitcnt vmcnt(0)" ::: "memory");
;             const unsigned og = xb_add(&bar[XB_TOP], 1u);
;             const unsigned tg = og / nx;
;             if (og + 1u == (tg + 1u) * nx) xb_add(&bar[XB_TOPGEN], 1u);
;             else XB_SPIN(xb_ld(&bar[XB_TOPGEN]) == tg, bar);
;             __builtin_amdgcn_fence(__ATOMIC_ACQUIRE, "agent");
;             xb_add(&bar[XB_XGEN(b.x)], 1u);
;             asm volatile("s_waitcnt vmcnt(0)" ::: "memory");
;         } else {
;             XB_SPIN(xb_ld(&bar[XB_XGEN(b.x)]) == gen, bar);
;             __builtin_amdgcn_fence(__ATOMIC_ACQUIRE, "agent");
;             asm volatile("s_waitcnt vmcnt(0)" ::: "memory");
;         }
.LBB0_1904:
	s_cmp_lt_i32 s57, 7
	s_cbranch_scc1 .LBB0_1958
	s_waitcnt vmcnt(0)
	s_waitcnt lgkmcnt(0)
	s_barrier
	s_and_saveexec_b64 s[6:7], s[4:5]
	s_cbranch_execz .LBB0_1957
	buffer_inv sc1
	v_mov_b32_e32 v0, 0
	global_load_dwordx4 v[6:9], v0, s[50:51] offset:256 sc1
	global_load_dwordx4 v[10:13], v0, s[50:51] offset:272 sc1
	s_lshl_b32 s3, s33, 8
	s_add_u32 s8, s50, s3
	s_addc_u32 s9, s51, 0
	v_mov_b32_e32 v3, 0x2000
	global_load_dword v4, v3, s[8:9] offset:1024 sc1
	v_mov_b32_e32 v2, 0x20000
	ds_read_b32 v2, v2
	s_waitcnt vmcnt(0) lgkmcnt(0)
	v_add_u32_e32 v14, -1, v6
	v_and_b32_e32 v1, v14, v6
	v_min_u32_e32 v15, v6, v7
	v_add_u32_e32 v14, -1, v7
	v_and_or_b32 v1, v14, v7, v1
	v_min_u32_e32 v15, v15, v8
	v_add_u32_e32 v14, -1, v8
	v_and_or_b32 v1, v14, v8, v1
	v_min_u32_e32 v15, v15, v9
	v_add_u32_e32 v14, -1, v9
	v_and_or_b32 v1, v14, v9, v1
	v_min_u32_e32 v15, v15, v10
	v_add_u32_e32 v14, -1, v10
	v_and_or_b32 v1, v14, v10, v1
	v_min_u32_e32 v15, v15, v11
	v_add_u32_e32 v14, -1, v11
	v_and_or_b32 v1, v14, v11, v1
	v_min_u32_e32 v15, v15, v12
	v_add_u32_e32 v14, -1, v12
	v_and_or_b32 v1, v14, v12, v1
	v_min_u32_e32 v15, v15, v13
	v_add_u32_e32 v14, -1, v13
	v_and_or_b32 v1, v14, v13, v1
	s_nop 0
	v_readfirstlane_b32 s10, v1
	v_readfirstlane_b32 s13, v15
	v_readfirstlane_b32 s11, v4
	v_readfirstlane_b32 s12, v2
	s_nop 1
	s_cmp_lg_u32 s10, 0
	s_cbranch_scc1 .Lseam56_full
	s_cmp_eq_u32 s13, 0
	s_cbranch_scc1 .Lseam56_full
	s_cmpk_lg_i32 s58, 0x100
	s_cbranch_scc1 .Lseam56_full
	s_cmp_eq_u32 s12, 0
	s_cbranch_scc1 .Lseam56_full
	v_mov_b32_e32 v3, 0x1000
	v_mov_b32_e32 v5, 1
	global_atomic_add v3, v3, v5, s[8:9] offset:1024 sc0
	s_waitcnt vmcnt(0)
	v_readfirstlane_b32 s13, v3
	s_add_i32 s14, s11, 1
	s_mul_i32 s14, s14, s12
	s_add_i32 s13, s13, 1
	v_mov_b32_e32 v3, 0x2000
	s_cmp_eq_u32 s13, s14
	s_cbranch_scc1 .Lseam56_lead

; __device__ __forceinline__ unsigned xb_ld(unsigned* p)              { return __hip_atomic_load(p, __ATOMIC_RELAXED, __HIP_MEMORY_SCOPE_AGENT); }
; __device__ __forceinline__ unsigned xb_add(unsigned* p, unsigned v) { return __hip_atomic_fetch_add(p, v, __ATOMIC_RELAXED, __HIP_MEMORY_SCOPE_AGENT); }
; #define XB_SPIN(cond, bar) do { unsigned _sp = 0; while (cond) { __builtin_amdgcn_s_sleep(1); \
;     if ((++_sp & 255u) == 0u) { if (xb_ld(&(bar)[XB_TMO])) break; if (_sp > XB_SPIN_CAP) { atomicAdd(&(bar)[XB_TMO], 1u); break; } } } } while (0)
; __device__ __forceinline__ void xcd_barrier(const XcdBarrier& b) {
;     asm volatile("s_waitcnt vmcnt(0)" ::: "memory");
;     __syncthreads();
;     if (threadIdx.x == 0) {
;         unsigned* bar = b.bar;
;         __builtin_amdgcn_s_waitcnt(0);
;         unsigned nloc = b.st[0], nx = b.st[1];
;         if (nloc == 0u) { xcd_barrier_complete(bar, b.x, nloc, nx); b.st[0] = nloc; b.st[1] = nx; }
;         const unsigned old = xb_add(&bar[XB_XSUB(b.x)], 1u);
;         const unsigned gen = old / nloc;
;         if (old + 1u == (gen + 1u) * nloc) {
;             __builtin_amdgcn_fence(__ATOMIC_RELEASE, "agent");
;             asm volatile("s_waitcnt vmcnt(0)" ::: "memory");
;             const unsigned og = xb_add(&bar[XB_TOP], 1u);
;             const unsigned tg = og / nx;
;             if (og + 1u == (tg + 1u) * nx) xb_add(&bar[XB_TOPGEN], 1u);
;             else XB_SPIN(xb_ld(&bar[XB_TOPGEN]) == tg, bar);
;             __builtin_amdgcn_fence(__ATOMIC_ACQUIRE, "agent");
;             xb_add(&bar[XB_XGEN(b.x)], 1u);
;             asm volatile("s_waitcnt vmcnt(0)" ::: "memory");
;         } else {
;             XB_SPIN(xb_ld(&bar[XB_XGEN(b.x)]) == gen, bar);
;             __builtin_amdgcn_fence(__ATOMIC_ACQUIRE, "agent");
;             asm volatile("s_waitcnt vmcnt(0)" ::: "memory");
;         }
.LBB0_2222:
	s_cmp_lt_i32 s57, 10
	s_cbranch_scc1 .LBB0_2276
	s_waitcnt vmcnt(0)
	s_barrier
	s_and_saveexec_b64 s[6:7], s[4:5]
	s_cbranch_execz .LBB0_2275
	buffer_inv sc1
	v_mov_b32_e32 v0, 0
	global_load_dwordx4 v[6:9], v0, s[50:51] offset:256 sc1
	global_load_dwordx4 v[10:13], v0, s[50:51] offset:272 sc1
	s_lshl_b32 s3, s33, 8
	s_add_u32 s8, s50, s3
	s_addc_u32 s9, s51, 0
	v_mov_b32_e32 v3, 0x2000
	global_load_dword v4, v3, s[8:9] offset:1024 sc1
	v_mov_b32_e32 v2, 0x20000
	ds_read_b32 v2, v2
	s_waitcnt vmcnt(0) lgkmcnt(0)
	v_add_u32_e32 v14, -1, v6
	v_and_b32_e32 v1, v14, v6
	v_min_u32_e32 v15, v6, v7
	v_add_u32_e32 v14, -1, v7
	v_and_or_b32 v1, v14, v7, v1
	v_min_u32_e32 v15, v15, v8
	v_add_u32_e32 v14, -1, v8
	v_and_or_b32 v1, v14, v8, v1
	v_min_u32_e32 v15, v15, v9
	v_add_u32_e32 v14, -1, v9
	v_and_or_b32 v1, v14, v9, v1
	v_min_u32_e32 v15, v15, v10
	v_add_u32_e32 v14, -1, v10
	v_and_or_b32 v1, v14, v10, v1
	v_min_u32_e32 v15, v15, v11
	v_add_u32_e32 v14, -1, v11
	v_and_or_b32 v1, v14, v11, v1
	v_min_u32_e32 v15, v15, v12
	v_add_u32_e32 v14, -1, v12
	v_and_or_b32 v1, v14, v12, v1
	v_min_u32_e32 v15, v15, v13
	v_add_u32_e32 v14, -1, v13
	v_and_or_b32 v1, v14, v13, v1
	s_nop 0
	v_readfirstlane_b32 s10, v1
	v_readfirstlane_b32 s13, v15
	v_readfirstlane_b32 s11, v4
	v_readfirstlane_b32 s12, v2
	s_nop 1
	s_cmp_lg_u32 s10, 0
	s_cbranch_scc1 .Lseam89_full
	s_cmp_eq_u32 s13, 0
	s_cbranch_scc1 .Lseam89_full
	s_cmpk_lg_i32 s58, 0x100
	s_cbranch_scc1 .Lseam89_full
	s_cmp_eq_u32 s12, 0
	s_cbranch_scc1 .Lseam89_full
	v_mov_b32_e32 v3, 0x1000
	v_mov_b32_e32 v5, 1
	global_atomic_add v3, v3, v5, s[8:9] offset:1024 sc0
	s_waitcnt vmcnt(0)
	v_readfirstlane_b32 s13, v3
	s_add_i32 s14, s11, 1
	s_mul_i32 s14, s14, s12
	s_add_i32 s13, s13, 1
	v_mov_b32_e32 v3, 0x2000
	s_cmp_eq_u32 s13, s14
	s_cbranch_scc1 .Lseam89_lead

; __device__ __forceinline__ unsigned xb_ld(unsigned* p)              { return __hip_atomic_load(p, __ATOMIC_RELAXED, __HIP_MEMORY_SCOPE_AGENT); }
; __device__ __forceinline__ unsigned xb_add(unsigned* p, unsigned v) { return __hip_atomic_fetch_add(p, v, __ATOMIC_RELAXED, __HIP_MEMORY_SCOPE_AGENT); }
; #define XB_SPIN(cond, bar) do { unsigned _sp = 0; while (cond) { __builtin_amdgcn_s_sleep(1); \
;     if ((++_sp & 255u) == 0u) { if (xb_ld(&(bar)[XB_TMO])) break; if (_sp > XB_SPIN_CAP) { atomicAdd(&(bar)[XB_TMO], 1u); break; } } } } while (0)
; __device__ __forceinline__ void xcd_barrier(const XcdBarrier& b) {
;     asm volatile("s_waitcnt vmcnt(0)" ::: "memory");
;     __syncthreads();
;     if (threadIdx.x == 0) {
;         unsigned* bar = b.bar;
;         __builtin_amdgcn_s_waitcnt(0);
;         unsigned nloc = b.st[0], nx = b.st[1];
;         if (nloc == 0u) { xcd_barrier_complete(bar, b.x, nloc, nx); b.st[0] = nloc; b.st[1] = nx; }
;         const unsigned old = xb_add(&bar[XB_XSUB(b.x)], 1u);
;         const unsigned gen = old / nloc;
;         if (old + 1u == (gen + 1u) * nloc) {
;             __builtin_amdgcn_fence(__ATOMIC_RELEASE, "agent");
;             asm volatile("s_waitcnt vmcnt(0)" ::: "memory");
;             const unsigned og = xb_add(&bar[XB_TOP], 1u);
;             const unsigned tg = og / nx;
;             if (og + 1u == (tg + 1u) * nx) xb_add(&bar[XB_TOPGEN], 1u);
;             else XB_SPIN(xb_ld(&bar[XB_TOPGEN]) == tg, bar);
;             __builtin_amdgcn_fence(__ATOMIC_ACQUIRE, "agent");
;             xb_add(&bar[XB_XGEN(b.x)], 1u);
;             asm volatile("s_waitcnt vmcnt(0)" ::: "memory");
;         } else {
;             XB_SPIN(xb_ld(&bar[XB_XGEN(b.x)]) == gen, bar);
;             __builtin_amdgcn_fence(__ATOMIC_ACQUIRE, "agent");
;             asm volatile("s_waitcnt vmcnt(0)" ::: "memory");
;         }
.LBB0_2546:
	s_cmp_lt_i32 s57, 13
	s_cbranch_scc1 .LBB0_2600
	s_waitcnt vmcnt(0)
	s_waitcnt lgkmcnt(0)
	s_barrier
	s_and_saveexec_b64 s[6:7], s[4:5]
	s_cbranch_execz .LBB0_2599
	buffer_inv sc1
	v_mov_b32_e32 v0, 0
	global_load_dwordx4 v[6:9], v0, s[50:51] offset:256 sc1
	global_load_dwordx4 v[10:13], v0, s[50:51] offset:272 sc1
	s_lshl_b32 s3, s33, 8
	s_add_u32 s8, s50, s3
	s_addc_u32 s9, s51, 0
	v_mov_b32_e32 v3, 0x2000
	global_load_dword v4, v3, s[8:9] offset:1024 sc1
	v_mov_b32_e32 v2, 0x20000
	ds_read_b32 v2, v2
	s_waitcnt vmcnt(0) lgkmcnt(0)
	v_add_u32_e32 v14, -1, v6
	v_and_b32_e32 v1, v14, v6
	v_min_u32_e32 v15, v6, v7
	v_add_u32_e32 v14, -1, v7
	v_and_or_b32 v1, v14, v7, v1
	v_min_u32_e32 v15, v15, v8
	v_add_u32_e32 v14, -1, v8
	v_and_or_b32 v1, v14, v8, v1
	v_min_u32_e32 v15, v15, v9
	v_add_u32_e32 v14, -1, v9
	v_and_or_b32 v1, v14, v9, v1
	v_min_u32_e32 v15, v15, v10
	v_add_u32_e32 v14, -1, v10
	v_and_or_b32 v1, v14, v10, v1
	v_min_u32_e32 v15, v15, v11
	v_add_u32_e32 v14, -1, v11
	v_and_or_b32 v1, v14, v11, v1
	v_min_u32_e32 v15, v15, v12
	v_add_u32_e32 v14, -1, v12
	v_and_or_b32 v1, v14, v12, v1
	v_min_u32_e32 v15, v15, v13
	v_add_u32_e32 v14, -1, v13
	v_and_or_b32 v1, v14, v13, v1
	s_nop 0
	v_readfirstlane_b32 s10, v1
	v_readfirstlane_b32 s13, v15
	v_readfirstlane_b32 s11, v4
	v_readfirstlane_b32 s12, v2
	s_nop 1
	s_cmp_lg_u32 s10, 0
	s_cbranch_scc1 .Lseam1112_full
	s_cmp_eq_u32 s13, 0
	s_cbranch_scc1 .Lseam1112_full
	s_cmpk_lg_i32 s58, 0x100
	s_cbranch_scc1 .Lseam1112_full
	s_cmp_eq_u32 s12, 0
	s_cbranch_scc1 .Lseam1112_full
	v_mov_b32_e32 v3, 0x1000
	v_mov_b32_e32 v5, 1
	global_atomic_add v3, v3, v5, s[8:9] offset:1024 sc0
	s_waitcnt vmcnt(0)
	v_readfirstlane_b32 s13, v3
	s_add_i32 s14, s11, 1
	s_mul_i32 s14, s14, s12
	s_add_i32 s13, s13, 1
	v_mov_b32_e32 v3, 0x2000
	s_cmp_eq_u32 s13, s14
	s_cbranch_scc1 .Lseam1112_lead
